# in-proj K-loop: s_sleep 1 at the start of every load section (lets the partner wave's MFMA section start unimpeded)
# speedup vs baseline: 1.0087x; 1.0075x over previous
; #define PG8_STAGE(bufoff, gbase, voff) do { _Pragma("unroll") for (int _i = 0; _i < 2; ++_i) \
;         __builtin_amdgcn_global_load_lds((const unsigned*)((const char*)(gbase) + (voff)[_i]), (LAS unsigned*)(lds + (bufoff) + ldsw + _i * 8192), 16, 0, 0); } while (0)
; #define PG8_LDA(dst, b, h) do { _Pragma("unroll") for (int m = 0; m < 4; ++m) _Pragma("unroll") for (int k = 0; k < 2; ++k) dst[m][k] = *(const LAS bf16x8*)(lds + PG8_SA(b, h) + aoff + m * 2048 + k * 1024); } while (0)
; #define PG8_LDB(dst, b, h) do { _Pragma("unroll") for (int n = 0; n < 2; ++n) _Pragma("unroll") for (int k = 0; k < 2; ++k) dst[n][k] = *(const LAS bf16x8*)(lds + PG8_SB(b, h) + boff + n * 2048 + k * 1024); } while (0)
; #define PG8_MMA(ai, bj, At, Bt) do { __builtin_amdgcn_s_setprio(1); _Pragma("unroll") for (int m = 0; m < 4; ++m) _Pragma("unroll") for (int n = 0; n < 2; ++n) _Pragma("unroll") for (int k = 0; k < 2; ++k) \
;         acc[ai][bj][m][n] = __builtin_amdgcn_mfma_f32_16x16x32_bf16(Bt[n][k], At[m][k], acc[ai][bj][m][n], 0, 0, 0); __builtin_amdgcn_s_setprio(0); } while (0)
; #define PG8_WAIT_V(n) asm volatile("s_waitcnt vmcnt(" #n ")" ::: "memory")
; #define PG8_WAIT_L(n) asm volatile("s_waitcnt lgkmcnt(" #n ")" ::: "memory")
; #define PG8_BAR __builtin_amdgcn_s_barrier()
; #define PG8_SCHED __builtin_amdgcn_sched_barrier(0)
; template <class Epi>
; __device__ __forceinline__ void gemm_phase(LAS unsigned char* lds, const Gemm g, const int G, const int cidx, const Epi& E) {
;     ...
;             const char* a1 = cA + (size_t)(t + 1) * kstep;
;             const char* a2 = last ? nA : cA + (size_t)(t + 2) * kstep; const char* b2 = last ? nB : cB + (size_t)(t + 2) * kstep;
;             const char* a3 = a2 + kstep; const char* b3 = b2 + kstep;
;             PG8_LDB(B0, 0, 0); PG8_LDB(B1, 0, 1); PG8_SCHED; PG8_LDA(At, 0, 0); PG8_STAGE(PG8_SA(1, 1), a1 + hstep, voffA);
;             PG8_WAIT_V(8); PG8_WAIT_L(0); PG8_BAR; PG8_MMA(0, 0, At, B0); PG8_MMA(0, 1, At, B1); PG8_BAR; PG8_SCHED;
;             PG8_LDA(At, 0, 1); PG8_STAGE(PG8_SB(0, 0), b2, voffB); PG8_STAGE(PG8_SB(0, 1), b2 + hstep, voffB); PG8_STAGE(PG8_SA(0, 0), a2, voffA);
;             PG8_WAIT_V(8); PG8_WAIT_L(0); PG8_BAR; PG8_MMA(1, 0, At, B0); PG8_MMA(1, 1, At, B1); PG8_BAR; PG8_SCHED;
.LBB0_601:
	s_add_u32 s24, s20, 0xfffc0080
	s_addc_u32 s25, s21, -1
	s_add_i32 s43, 0, 0x10000
	s_cmp_eq_u32 s45, 12
	s_cselect_b32 s27, s11, s25
	s_cselect_b32 s26, s19, s24
	v_add_u32_e32 v132, s43, v145
	s_cselect_b32 s25, s9, s44
	s_cselect_b32 s24, s33, s42
	s_add_i32 s68, 0, 0x14000
	ds_read_b128 v[158:161], v132
	ds_read_b128 v[164:167], v132 offset:1024
	ds_read_b128 v[168:171], v132 offset:2048
	ds_read_b128 v[172:175], v132 offset:3072
	v_add_u32_e32 v132, s68, v145
	ds_read_b128 v[176:179], v132
	ds_read_b128 v[180:183], v132 offset:1024
	ds_read_b128 v[184:187], v132 offset:2048
	ds_read_b128 v[188:191], v132 offset:3072
	v_lshl_add_u64 v[132:133], s[20:21], 0, v[156:157]
	s_add_i32 m0, s97, 0xc000
	ds_read_b128 v[192:195], v163
	ds_read_b128 v[196:199], v163 offset:1024
	ds_read_b128 v[214:217], v163 offset:2048
	ds_read_b128 v[218:221], v163 offset:3072
	ds_read_b128 v[222:225], v163 offset:4096
	ds_read_b128 v[226:229], v163 offset:5120
	ds_read_b128 v[230:233], v163 offset:6144
	ds_read_b128 v[234:237], v163 offset:7168
	global_load_lds_dwordx4 v[132:133], off
	v_lshl_add_u64 v[132:133], s[20:21], 0, v[154:155]
	s_add_i32 m0, s97, 0xe000
	s_nop 0
	global_load_lds_dwordx4 v[132:133], off
	s_waitcnt vmcnt(8)
	s_waitcnt lgkmcnt(0)
	s_barrier
	s_setprio 1
	s_waitcnt lgkmcnt(0)
	v_mfma_f32_16x16x32_bf16 v[128:131], v[158:161], v[192:195], v[128:131]
	v_mfma_f32_16x16x32_bf16 v[124:127], v[168:171], v[192:195], v[124:127]
	v_mfma_f32_16x16x32_bf16 v[120:123], v[158:161], v[214:217], v[120:123]
	v_mfma_f32_16x16x32_bf16 v[112:115], v[168:171], v[214:217], v[112:115]
	v_mfma_f32_16x16x32_bf16 v[104:107], v[158:161], v[222:225], v[104:107]
	v_mfma_f32_16x16x32_bf16 v[96:99], v[168:171], v[222:225], v[96:99]
	v_mfma_f32_16x16x32_bf16 v[88:91], v[158:161], v[230:233], v[88:91]
	v_mfma_f32_16x16x32_bf16 v[80:83], v[168:171], v[230:233], v[80:83]
	v_mfma_f32_16x16x32_bf16 v[128:131], v[164:167], v[196:199], v[128:131]
	v_mfma_f32_16x16x32_bf16 v[124:127], v[172:175], v[196:199], v[124:127]
	v_mfma_f32_16x16x32_bf16 v[120:123], v[164:167], v[218:221], v[120:123]
	v_mfma_f32_16x16x32_bf16 v[112:115], v[172:175], v[218:221], v[112:115]
	v_mfma_f32_16x16x32_bf16 v[104:107], v[164:167], v[226:229], v[104:107]
	v_mfma_f32_16x16x32_bf16 v[96:99], v[172:175], v[226:229], v[96:99]
	v_mfma_f32_16x16x32_bf16 v[88:91], v[164:167], v[234:237], v[88:91]
	v_mfma_f32_16x16x32_bf16 v[80:83], v[172:175], v[234:237], v[80:83]
	s_setprio 0
	s_setprio 1
	v_mfma_f32_16x16x32_bf16 v[116:119], v[176:179], v[192:195], v[116:119]
	v_mfma_f32_16x16x32_bf16 v[108:111], v[184:187], v[192:195], v[108:111]
	v_mfma_f32_16x16x32_bf16 v[100:103], v[176:179], v[214:217], v[100:103]
	v_mfma_f32_16x16x32_bf16 v[92:95], v[184:187], v[214:217], v[92:95]
	v_mfma_f32_16x16x32_bf16 v[84:87], v[176:179], v[222:225], v[84:87]
	v_mfma_f32_16x16x32_bf16 v[76:79], v[184:187], v[222:225], v[76:79]
	v_mfma_f32_16x16x32_bf16 v[72:75], v[176:179], v[230:233], v[72:75]
	v_mfma_f32_16x16x32_bf16 v[68:71], v[184:187], v[230:233], v[68:71]
	v_mfma_f32_16x16x32_bf16 v[116:119], v[180:183], v[196:199], v[116:119]
	v_mfma_f32_16x16x32_bf16 v[108:111], v[188:191], v[196:199], v[108:111]
	v_mfma_f32_16x16x32_bf16 v[100:103], v[180:183], v[218:221], v[100:103]
	v_mfma_f32_16x16x32_bf16 v[92:95], v[188:191], v[218:221], v[92:95]
	v_mfma_f32_16x16x32_bf16 v[84:87], v[180:183], v[226:229], v[84:87]
	v_mfma_f32_16x16x32_bf16 v[76:79], v[188:191], v[226:229], v[76:79]
	v_mfma_f32_16x16x32_bf16 v[72:75], v[180:183], v[234:237], v[72:75]
	v_mfma_f32_16x16x32_bf16 v[68:71], v[188:191], v[234:237], v[68:71]
	s_setprio 0
	s_barrier
	s_sleep 1
	s_add_i32 s43, s43, s95
	v_lshl_add_u64 v[132:133], s[24:25], 0, v[148:149]
	s_mov_b32 m0, s43
	ds_read_b128 v[192:195], v163 offset:16384
	ds_read_b128 v[196:199], v163 offset:17408
	ds_read_b128 v[214:217], v163 offset:18432
	ds_read_b128 v[218:221], v163 offset:19456
	ds_read_b128 v[222:225], v163 offset:20480
	ds_read_b128 v[226:229], v163 offset:21504
	ds_read_b128 v[230:233], v163 offset:22528
	ds_read_b128 v[234:237], v163 offset:23552
	global_load_lds_dwordx4 v[132:133], off
	s_add_i32 m0, s43, 0x2000
	s_add_u32 s86, s24, 0x40000
	v_lshl_add_u64 v[134:135], s[24:25], 0, v[0:1]
	s_addc_u32 s87, s25, 0
	s_add_i32 s43, s68, s95
	global_load_lds_dwordx4 v[134:135], off
	v_lshl_add_u64 v[140:141], s[86:87], 0, v[148:149]
	s_mov_b32 m0, s43
	v_lshl_add_u64 v[142:143], s[26:27], 0, v[146:147]
	global_load_lds_dwordx4 v[140:141], off
	v_lshl_add_u64 v[140:141], s[86:87], 0, v[0:1]
	s_add_i32 m0, s43, 0x2000
	s_nop 0
	global_load_lds_dwordx4 v[140:141], off
	v_lshl_add_u64 v[140:141], s[26:27], 0, v[150:151]
	s_mov_b32 m0, s97
	s_nop 0
	global_load_lds_dwordx4 v[140:141], off
	s_mov_b32 m0, s22
	s_nop 0
	global_load_lds_dwordx4 v[142:143], off
	s_waitcnt vmcnt(8)
	s_waitcnt lgkmcnt(0)
	s_barrier
; #define PG8_STAGE(bufoff, gbase, voff) do { _Pragma("unroll") for (int _i = 0; _i < 2; ++_i) \
;         __builtin_amdgcn_global_load_lds((const unsigned*)((const char*)(gbase) + (voff)[_i]), (LAS unsigned*)(lds + (bufoff) + ldsw + _i * 8192), 16, 0, 0); } while (0)
; #define PG8_LDA(dst, b, h) do { _Pragma("unroll") for (int m = 0; m < 4; ++m) _Pragma("unroll") for (int k = 0; k < 2; ++k) dst[m][k] = *(const LAS bf16x8*)(lds + PG8_SA(b, h) + aoff + m * 2048 + k * 1024); } while (0)
; #define PG8_LDB(dst, b, h) do { _Pragma("unroll") for (int n = 0; n < 2; ++n) _Pragma("unroll") for (int k = 0; k < 2; ++k) dst[n][k] = *(const LAS bf16x8*)(lds + PG8_SB(b, h) + boff + n * 2048 + k * 1024); } while (0)
; #define PG8_MMA(ai, bj, At, Bt) do { __builtin_amdgcn_s_setprio(1); _Pragma("unroll") for (int m = 0; m < 4; ++m) _Pragma("unroll") for (int n = 0; n < 2; ++n) _Pragma("unroll") for (int k = 0; k < 2; ++k) \
;         acc[ai][bj][m][n] = __builtin_amdgcn_mfma_f32_16x16x32_bf16(Bt[n][k], At[m][k], acc[ai][bj][m][n], 0, 0, 0); __builtin_amdgcn_s_setprio(0); } while (0)
; #define PG8_WAIT_V(n) asm volatile("s_waitcnt vmcnt(" #n ")" ::: "memory")
; #define PG8_WAIT_L(n) asm volatile("s_waitcnt lgkmcnt(" #n ")" ::: "memory")
; #define PG8_BAR __builtin_amdgcn_s_barrier()
; #define PG8_SCHED __builtin_amdgcn_sched_barrier(0)
; template <class Epi>
; __device__ __forceinline__ void gemm_phase(LAS unsigned char* lds, const Gemm g, const int G, const int cidx, const Epi& E) {
;     ...
;             PG8_WAIT_V(8); PG8_WAIT_L(0); PG8_BAR; PG8_MMA(1, 0, At, B0); PG8_MMA(1, 1, At, B1); PG8_BAR; PG8_SCHED;
;             PG8_LDB(B0, 1, 0); PG8_LDB(B1, 1, 1); PG8_SCHED; PG8_LDA(At, 1, 0); PG8_STAGE(PG8_SA(0, 1), a2 + hstep, voffA);
;             PG8_WAIT_V(8); PG8_WAIT_L(0); PG8_BAR; PG8_MMA(0, 0, At, B0); PG8_MMA(0, 1, At, B1); PG8_BAR; PG8_SCHED;
	s_setprio 1
	s_waitcnt lgkmcnt(0)
	v_mfma_f32_16x16x32_bf16 v[64:67], v[158:161], v[192:195], v[64:67]
	v_mfma_f32_16x16x32_bf16 v[60:63], v[168:171], v[192:195], v[60:63]
	v_mfma_f32_16x16x32_bf16 v[56:59], v[158:161], v[214:217], v[56:59]
	v_mfma_f32_16x16x32_bf16 v[48:51], v[168:171], v[214:217], v[48:51]
	v_mfma_f32_16x16x32_bf16 v[40:43], v[158:161], v[222:225], v[40:43]
	v_mfma_f32_16x16x32_bf16 v[32:35], v[168:171], v[222:225], v[32:35]
	v_mfma_f32_16x16x32_bf16 v[24:27], v[158:161], v[230:233], v[24:27]
	v_mfma_f32_16x16x32_bf16 v[16:19], v[168:171], v[230:233], v[16:19]
	v_mfma_f32_16x16x32_bf16 v[64:67], v[164:167], v[196:199], v[64:67]
	v_mfma_f32_16x16x32_bf16 v[60:63], v[172:175], v[196:199], v[60:63]
	v_mfma_f32_16x16x32_bf16 v[56:59], v[164:167], v[218:221], v[56:59]
	v_mfma_f32_16x16x32_bf16 v[48:51], v[172:175], v[218:221], v[48:51]
	v_mfma_f32_16x16x32_bf16 v[40:43], v[164:167], v[226:229], v[40:43]
	v_mfma_f32_16x16x32_bf16 v[32:35], v[172:175], v[226:229], v[32:35]
	v_mfma_f32_16x16x32_bf16 v[24:27], v[164:167], v[234:237], v[24:27]
	v_mfma_f32_16x16x32_bf16 v[16:19], v[172:175], v[234:237], v[16:19]
	s_setprio 0
	s_setprio 1
	v_mfma_f32_16x16x32_bf16 v[52:55], v[176:179], v[192:195], v[52:55]
	v_mfma_f32_16x16x32_bf16 v[44:47], v[184:187], v[192:195], v[44:47]
	v_mfma_f32_16x16x32_bf16 v[36:39], v[176:179], v[214:217], v[36:39]
	v_mfma_f32_16x16x32_bf16 v[28:31], v[184:187], v[214:217], v[28:31]
	v_mfma_f32_16x16x32_bf16 v[20:23], v[176:179], v[222:225], v[20:23]
	v_mfma_f32_16x16x32_bf16 v[12:15], v[184:187], v[222:225], v[12:15]
	v_mfma_f32_16x16x32_bf16 v[8:11], v[176:179], v[230:233], v[8:11]
	v_mfma_f32_16x16x32_bf16 v[4:7], v[184:187], v[230:233], v[4:7]
	v_mfma_f32_16x16x32_bf16 v[52:55], v[180:183], v[196:199], v[52:55]
	v_mfma_f32_16x16x32_bf16 v[44:47], v[188:191], v[196:199], v[44:47]
	v_mfma_f32_16x16x32_bf16 v[36:39], v[180:183], v[218:221], v[36:39]
	v_mfma_f32_16x16x32_bf16 v[28:31], v[188:191], v[218:221], v[28:31]
	v_mfma_f32_16x16x32_bf16 v[20:23], v[180:183], v[226:229], v[20:23]
	v_mfma_f32_16x16x32_bf16 v[12:15], v[188:191], v[226:229], v[12:15]
	v_mfma_f32_16x16x32_bf16 v[8:11], v[180:183], v[234:237], v[8:11]
	v_mfma_f32_16x16x32_bf16 v[4:7], v[188:191], v[234:237], v[4:7]
	s_setprio 0
	s_barrier
	s_sleep 1
	s_add_i32 s43, 0, 0x18000
	s_add_i32 s68, 0, 0x1c000
	v_add_u32_e32 v172, s43, v145
	v_add_u32_e32 v188, s68, v145
	ds_read_b128 v[158:161], v172
	ds_read_b128 v[164:167], v172 offset:1024
	ds_read_b128 v[168:171], v172 offset:2048
	ds_read_b128 v[172:175], v172 offset:3072
	ds_read_b128 v[176:179], v188
	ds_read_b128 v[180:183], v188 offset:1024
	ds_read_b128 v[184:187], v188 offset:2048
	ds_read_b128 v[188:191], v188 offset:3072
	s_add_u32 s26, s26, 0x40000
	s_addc_u32 s27, s27, 0
	s_mov_b32 m0, s16
	v_lshl_add_u64 v[200:201], s[26:27], 0, v[150:151]
	ds_read_b128 v[192:195], v163 offset:32768
	ds_read_b128 v[196:199], v163 offset:33792
	ds_read_b128 v[214:217], v163 offset:34816
	ds_read_b128 v[218:221], v163 offset:35840
	ds_read_b128 v[222:225], v163 offset:36864
	ds_read_b128 v[226:229], v163 offset:37888
	ds_read_b128 v[230:233], v163 offset:38912
	ds_read_b128 v[234:237], v163 offset:39936
	global_load_lds_dwordx4 v[200:201], off
	v_lshl_add_u64 v[200:201], s[26:27], 0, v[146:147]
	s_mov_b32 m0, s17
	s_nop 0
	global_load_lds_dwordx4 v[200:201], off
	s_waitcnt vmcnt(8)
	s_waitcnt lgkmcnt(0)
	s_barrier
	s_setprio 1
	s_waitcnt lgkmcnt(0)
	v_mfma_f32_16x16x32_bf16 v[128:131], v[158:161], v[192:195], v[128:131]
	v_mfma_f32_16x16x32_bf16 v[124:127], v[168:171], v[192:195], v[124:127]
	v_mfma_f32_16x16x32_bf16 v[120:123], v[158:161], v[214:217], v[120:123]
	v_mfma_f32_16x16x32_bf16 v[112:115], v[168:171], v[214:217], v[112:115]
	v_mfma_f32_16x16x32_bf16 v[104:107], v[158:161], v[222:225], v[104:107]
	v_mfma_f32_16x16x32_bf16 v[96:99], v[168:171], v[222:225], v[96:99]
	v_mfma_f32_16x16x32_bf16 v[88:91], v[158:161], v[230:233], v[88:91]
	v_mfma_f32_16x16x32_bf16 v[80:83], v[168:171], v[230:233], v[80:83]
	v_mfma_f32_16x16x32_bf16 v[128:131], v[164:167], v[196:199], v[128:131]
	v_mfma_f32_16x16x32_bf16 v[124:127], v[172:175], v[196:199], v[124:127]
	v_mfma_f32_16x16x32_bf16 v[120:123], v[164:167], v[218:221], v[120:123]
	v_mfma_f32_16x16x32_bf16 v[112:115], v[172:175], v[218:221], v[112:115]
	v_mfma_f32_16x16x32_bf16 v[104:107], v[164:167], v[226:229], v[104:107]
	v_mfma_f32_16x16x32_bf16 v[96:99], v[172:175], v[226:229], v[96:99]
	v_mfma_f32_16x16x32_bf16 v[88:91], v[164:167], v[234:237], v[88:91]
	v_mfma_f32_16x16x32_bf16 v[80:83], v[172:175], v[234:237], v[80:83]
	s_setprio 0
	s_setprio 1
	v_mfma_f32_16x16x32_bf16 v[116:119], v[176:179], v[192:195], v[116:119]
	v_mfma_f32_16x16x32_bf16 v[108:111], v[184:187], v[192:195], v[108:111]
	v_mfma_f32_16x16x32_bf16 v[100:103], v[176:179], v[214:217], v[100:103]
	v_mfma_f32_16x16x32_bf16 v[92:95], v[184:187], v[214:217], v[92:95]
	v_mfma_f32_16x16x32_bf16 v[84:87], v[176:179], v[222:225], v[84:87]
	v_mfma_f32_16x16x32_bf16 v[76:79], v[184:187], v[222:225], v[76:79]
	v_mfma_f32_16x16x32_bf16 v[72:75], v[176:179], v[230:233], v[72:75]
	v_mfma_f32_16x16x32_bf16 v[68:71], v[184:187], v[230:233], v[68:71]
	v_mfma_f32_16x16x32_bf16 v[116:119], v[180:183], v[196:199], v[116:119]
	v_mfma_f32_16x16x32_bf16 v[108:111], v[188:191], v[196:199], v[108:111]
	v_mfma_f32_16x16x32_bf16 v[100:103], v[180:183], v[218:221], v[100:103]
	v_mfma_f32_16x16x32_bf16 v[92:95], v[188:191], v[218:221], v[92:95]
	v_mfma_f32_16x16x32_bf16 v[84:87], v[180:183], v[226:229], v[84:87]
	v_mfma_f32_16x16x32_bf16 v[76:79], v[188:191], v[226:229], v[76:79]
	v_mfma_f32_16x16x32_bf16 v[72:75], v[180:183], v[234:237], v[72:75]
	v_mfma_f32_16x16x32_bf16 v[68:71], v[188:191], v[234:237], v[68:71]
	s_setprio 0
	s_barrier
; #define PG8_STAGE(bufoff, gbase, voff) do { _Pragma("unroll") for (int _i = 0; _i < 2; ++_i) \
;         __builtin_amdgcn_global_load_lds((const unsigned*)((const char*)(gbase) + (voff)[_i]), (LAS unsigned*)(lds + (bufoff) + ldsw + _i * 8192), 16, 0, 0); } while (0)
; #define PG8_LDA(dst, b, h) do { _Pragma("unroll") for (int m = 0; m < 4; ++m) _Pragma("unroll") for (int k = 0; k < 2; ++k) dst[m][k] = *(const LAS bf16x8*)(lds + PG8_SA(b, h) + aoff + m * 2048 + k * 1024); } while (0)
; #define PG8_MMA(ai, bj, At, Bt) do { __builtin_amdgcn_s_setprio(1); _Pragma("unroll") for (int m = 0; m < 4; ++m) _Pragma("unroll") for (int n = 0; n < 2; ++n) _Pragma("unroll") for (int k = 0; k < 2; ++k) \
;         acc[ai][bj][m][n] = __builtin_amdgcn_mfma_f32_16x16x32_bf16(Bt[n][k], At[m][k], acc[ai][bj][m][n], 0, 0, 0); __builtin_amdgcn_s_setprio(0); } while (0)
; #define PG8_WAIT_V(n) asm volatile("s_waitcnt vmcnt(" #n ")" ::: "memory")
; #define PG8_WAIT_L(n) asm volatile("s_waitcnt lgkmcnt(" #n ")" ::: "memory")
; #define PG8_BAR __builtin_amdgcn_s_barrier()
; #define PG8_SCHED __builtin_amdgcn_sched_barrier(0)
; template <class Epi>
; __device__ __forceinline__ void gemm_phase(LAS unsigned char* lds, const Gemm g, const int G, const int cidx, const Epi& E) {
;     ...
;             PG8_LDA(At, 1, 1); PG8_STAGE(PG8_SB(1, 0), b3, voffB); PG8_STAGE(PG8_SB(1, 1), b3 + hstep, voffB); PG8_STAGE(PG8_SA(1, 0), a3, voffA);
;             PG8_WAIT_V(8); PG8_WAIT_L(0); PG8_BAR; PG8_MMA(1, 0, At, B0); PG8_MMA(1, 1, At, B1); PG8_BAR; PG8_SCHED;
;         }
;         if constexpr (!Epi::AFTER_DRAIN) E(acc, cur, wr, wc, fr, fq);
	s_sleep 1
	s_add_i32 s26, s43, s95
	v_lshl_add_u64 v[132:133], v[132:133], 0, s[46:47]
	s_mov_b32 m0, s26
	ds_read_b128 v[192:195], v163 offset:49152
	ds_read_b128 v[196:199], v163 offset:50176
	ds_read_b128 v[214:217], v163 offset:51200
	ds_read_b128 v[218:221], v163 offset:52224
	ds_read_b128 v[222:225], v163 offset:53248
	ds_read_b128 v[226:229], v163 offset:54272
	ds_read_b128 v[230:233], v163 offset:55296
	ds_read_b128 v[234:237], v163 offset:56320
	global_load_lds_dwordx4 v[132:133], off
	s_add_i32 m0, s26, 0x2000
	s_add_u32 s24, s24, 0x40080
	v_lshl_add_u64 v[132:133], v[134:135], 0, s[46:47]
	s_addc_u32 s25, s25, 0
	s_add_i32 s26, s68, s95
	global_load_lds_dwordx4 v[132:133], off
	v_lshl_add_u64 v[132:133], s[24:25], 0, v[148:149]
	s_mov_b32 m0, s26
	s_nop 0
	global_load_lds_dwordx4 v[132:133], off
	v_lshl_add_u64 v[132:133], s[24:25], 0, v[0:1]
	s_add_i32 m0, s26, 0x2000
	s_nop 0
	global_load_lds_dwordx4 v[132:133], off
	v_lshl_add_u64 v[132:133], v[140:141], 0, s[46:47]
	s_mov_b32 m0, s84
	s_nop 0
	global_load_lds_dwordx4 v[132:133], off
	v_lshl_add_u64 v[132:133], v[142:143], 0, s[46:47]
	s_mov_b32 m0, s76
	s_nop 0
	global_load_lds_dwordx4 v[132:133], off
	s_waitcnt vmcnt(8)
	s_waitcnt lgkmcnt(0)
	s_barrier
	s_setprio 1
	s_waitcnt lgkmcnt(0)
	v_mfma_f32_16x16x32_bf16 v[64:67], v[158:161], v[192:195], v[64:67]
	v_mfma_f32_16x16x32_bf16 v[60:63], v[168:171], v[192:195], v[60:63]
	v_mfma_f32_16x16x32_bf16 v[56:59], v[158:161], v[214:217], v[56:59]
	v_mfma_f32_16x16x32_bf16 v[48:51], v[168:171], v[214:217], v[48:51]
	v_mfma_f32_16x16x32_bf16 v[40:43], v[158:161], v[222:225], v[40:43]
	v_mfma_f32_16x16x32_bf16 v[32:35], v[168:171], v[222:225], v[32:35]
	v_mfma_f32_16x16x32_bf16 v[24:27], v[158:161], v[230:233], v[24:27]
	v_mfma_f32_16x16x32_bf16 v[16:19], v[168:171], v[230:233], v[16:19]
	v_mfma_f32_16x16x32_bf16 v[64:67], v[164:167], v[196:199], v[64:67]
	v_mfma_f32_16x16x32_bf16 v[60:63], v[172:175], v[196:199], v[60:63]
	v_mfma_f32_16x16x32_bf16 v[56:59], v[164:167], v[218:221], v[56:59]
	v_mfma_f32_16x16x32_bf16 v[48:51], v[172:175], v[218:221], v[48:51]
	v_mfma_f32_16x16x32_bf16 v[40:43], v[164:167], v[226:229], v[40:43]
	v_mfma_f32_16x16x32_bf16 v[32:35], v[172:175], v[226:229], v[32:35]
	v_mfma_f32_16x16x32_bf16 v[24:27], v[164:167], v[234:237], v[24:27]
	v_mfma_f32_16x16x32_bf16 v[16:19], v[172:175], v[234:237], v[16:19]
	s_setprio 0
	s_setprio 1
	v_mfma_f32_16x16x32_bf16 v[52:55], v[176:179], v[192:195], v[52:55]
	v_mfma_f32_16x16x32_bf16 v[44:47], v[184:187], v[192:195], v[44:47]
	v_mfma_f32_16x16x32_bf16 v[36:39], v[176:179], v[214:217], v[36:39]
	v_mfma_f32_16x16x32_bf16 v[28:31], v[184:187], v[214:217], v[28:31]
	v_mfma_f32_16x16x32_bf16 v[20:23], v[176:179], v[222:225], v[20:23]
	v_mfma_f32_16x16x32_bf16 v[12:15], v[184:187], v[222:225], v[12:15]
	v_mfma_f32_16x16x32_bf16 v[8:11], v[176:179], v[230:233], v[8:11]
	v_mfma_f32_16x16x32_bf16 v[4:7], v[184:187], v[230:233], v[4:7]
	v_mfma_f32_16x16x32_bf16 v[52:55], v[180:183], v[196:199], v[52:55]
	v_mfma_f32_16x16x32_bf16 v[44:47], v[188:191], v[196:199], v[44:47]
	v_mfma_f32_16x16x32_bf16 v[36:39], v[180:183], v[218:221], v[36:39]
	v_mfma_f32_16x16x32_bf16 v[28:31], v[188:191], v[218:221], v[28:31]
	v_mfma_f32_16x16x32_bf16 v[20:23], v[180:183], v[226:229], v[20:23]
	v_mfma_f32_16x16x32_bf16 v[12:15], v[188:191], v[226:229], v[12:15]
	v_mfma_f32_16x16x32_bf16 v[8:11], v[180:183], v[234:237], v[8:11]
	v_mfma_f32_16x16x32_bf16 v[4:7], v[188:191], v[234:237], v[4:7]
	s_setprio 0
	s_barrier
	s_sleep 1
	s_add_i32 s45, s45, 2
	s_add_u32 s42, s42, 0x100
	s_addc_u32 s44, s44, 0
	s_add_u32 s20, s20, 0x100
	s_addc_u32 s21, s21, 0
	s_cmp_gt_u32 s45, 13
	s_cbranch_scc0 .LBB0_601
	s_cmp_gt_i32 s35, 10
	s_mov_b64 s[20:21], -1
	s_mov_b32 s26, 0x1a000
	s_mov_b32 s27, 0x19000
	s_cbranch_scc0 .LBB0_604
; __device__ __forceinline__ unsigned pk2(float lo, float hi) { unsigned r; asm("v_cvt_pk_bf16_f32 %0, %1, %2" : "=v"(r) : "v"(lo), "v"(hi)); return r; }
;     __device__ __forceinline__ void operator()(const f32x4 (&acc)[2][2][4][2], const Unit& u, int wr, int wc, int fr, int fq) const {
;     ...
;             const int g = u.pn - 11, n = g >> 2, q = g & 3;
;             bf16_t* blk = Gt + (((size_t)n * 64 + u.pm) * 8 + q * 2) * 32768 + (size_t)((wr * 4 * 4 + wc) * 64 + fq * 16 + fr) * 8;
; #pragma unroll
;             for (int ai = 0; ai < 2; ++ai)
; #pragma unroll
;                 for (int m = 0; m < 4; ++m)
; #pragma unroll
;                     for (int bj = 0; bj < 2; ++bj) { const f32x4 v0 = acc[ai][bj][m][0], v1 = acc[ai][bj][m][1];
;                         u32x4 w; w.x = pk2(v0[0], v0[1]); w.y = pk2(v0[2], v0[3]); w.z = pk2(v1[0], v1[1]); w.w = pk2(v1[2], v1[3]);
;                         *(u32x4*)(blk + (size_t)bj * 32768 + (size_t)((ai * 8 + m) * 4) * 512) = w; }
	s_add_i32 s9, s35, -11
	s_mov_b32 s21, s77
	s_lshr_b32 s20, s9, 2
	s_ashr_i32 s19, s18, 31
	s_lshl_b64 s[20:21], s[20:21], 9
	s_lshl_b64 s[24:25], s[18:19], 3
	s_add_u32 s11, s20, s24
	s_addc_u32 s21, s21, s25
	s_lshl_b32 s9, s9, 1
	s_and_b32 s9, s9, 6
	s_or_b32 s20, s11, s9
	s_lshl_b64 s[20:21], s[20:21], 16
	v_lshl_add_u64 v[158:159], v[152:153], 0, s[20:21]
	s_mov_b32 s9, 0x11000
	v_add_co_u32_e32 v132, vcc, s9, v158
	v_cvt_pk_bf16_f32 v164, v128, v129
	v_cvt_pk_bf16_f32 v165, v130, v131
	v_cvt_pk_bf16_f32 v166, v124, v125
	v_cvt_pk_bf16_f32 v167, v126, v127
	s_nop 1
	v_addc_co_u32_e32 v133, vcc, 0, v159, vcc
	global_store_dwordx4 v[158:159], v[164:167], off
	v_add_co_u32_e32 v134, vcc, s81, v158
	s_nop 0
	v_cvt_pk_bf16_f32 v164, v116, v117
	v_cvt_pk_bf16_f32 v165, v118, v119
	v_cvt_pk_bf16_f32 v166, v108, v109
	v_cvt_pk_bf16_f32 v167, v110, v111
	global_store_dwordx4 v[132:133], v[164:167], off offset:-4096
	v_addc_co_u32_e32 v135, vcc, 0, v159, vcc
	s_nop 0
	v_cvt_pk_bf16_f32 v164, v120, v121
	v_cvt_pk_bf16_f32 v165, v122, v123
	v_cvt_pk_bf16_f32 v166, v112, v113
	v_cvt_pk_bf16_f32 v167, v114, v115
	s_mov_b32 s9, 0x13000
	global_store_dwordx4 v[134:135], v[164:167], off offset:-4096
	s_mov_b64 s[20:21], 0
	s_nop 0
	v_cvt_pk_bf16_f32 v164, v100, v101
	v_cvt_pk_bf16_f32 v165, v102, v103
	v_cvt_pk_bf16_f32 v166, v92, v93
	v_cvt_pk_bf16_f32 v167, v94, v95
	global_store_dwordx4 v[132:133], v[164:167], off
	v_add_co_u32_e32 v132, vcc, s9, v158
	s_nop 0
	v_cvt_pk_bf16_f32 v164, v104, v105
	v_cvt_pk_bf16_f32 v165, v106, v107
	v_cvt_pk_bf16_f32 v166, v96, v97
	v_cvt_pk_bf16_f32 v167, v98, v99
	s_nop 0
	v_addc_co_u32_e32 v133, vcc, 0, v159, vcc
	global_store_dwordx4 v[134:135], v[164:167], off
	v_add_co_u32_e32 v134, vcc, s82, v158
	s_nop 0
	v_cvt_pk_bf16_f32 v164, v84, v85
	v_cvt_pk_bf16_f32 v165, v86, v87
	v_cvt_pk_bf16_f32 v166, v76, v77
	v_cvt_pk_bf16_f32 v167, v78, v79
	global_store_dwordx4 v[132:133], v[164:167], off offset:-4096
	v_addc_co_u32_e32 v135, vcc, 0, v159, vcc
	s_nop 0
	v_cvt_pk_bf16_f32 v164, v88, v89
	v_cvt_pk_bf16_f32 v165, v90, v91
	v_cvt_pk_bf16_f32 v166, v80, v81
	v_cvt_pk_bf16_f32 v167, v82, v83
	s_mov_b32 s9, 0x9000
	global_store_dwordx4 v[134:135], v[164:167], off
	s_nop 1
	v_cvt_pk_bf16_f32 v164, v72, v73
	v_cvt_pk_bf16_f32 v165, v74, v75
	v_cvt_pk_bf16_f32 v166, v68, v69
	v_cvt_pk_bf16_f32 v167, v70, v71
	global_store_dwordx4 v[132:133], v[164:167], off
	v_add_co_u32_e32 v132, vcc, s9, v158
	s_nop 0
	v_cvt_pk_bf16_f32 v164, v64, v65
	v_cvt_pk_bf16_f32 v165, v66, v67
	v_cvt_pk_bf16_f32 v166, v60, v61
	v_cvt_pk_bf16_f32 v167, v62, v63
	s_nop 0
	v_addc_co_u32_e32 v133, vcc, 0, v159, vcc
	v_add_co_u32_e32 v134, vcc, s27, v158
	global_store_dwordx4 v[132:133], v[164:167], off offset:-4096
	s_nop 0
	v_addc_co_u32_e32 v135, vcc, 0, v159, vcc
	v_cvt_pk_bf16_f32 v164, v52, v53
	v_cvt_pk_bf16_f32 v165, v54, v55
	v_cvt_pk_bf16_f32 v166, v44, v45
	v_cvt_pk_bf16_f32 v167, v46, v47
	s_mov_b32 s9, 0xb000
	global_store_dwordx4 v[134:135], v[164:167], off offset:-4096
	s_nop 1
	v_cvt_pk_bf16_f32 v164, v56, v57
	v_cvt_pk_bf16_f32 v165, v58, v59
	v_cvt_pk_bf16_f32 v166, v48, v49
	v_cvt_pk_bf16_f32 v167, v50, v51
	global_store_dwordx4 v[132:133], v[164:167], off
	v_add_co_u32_e32 v132, vcc, s9, v158
	s_nop 0
	v_cvt_pk_bf16_f32 v164, v36, v37
	v_cvt_pk_bf16_f32 v165, v38, v39
	v_cvt_pk_bf16_f32 v166, v28, v29
	v_cvt_pk_bf16_f32 v167, v30, v31
	s_nop 0
	v_addc_co_u32_e32 v133, vcc, 0, v159, vcc
	global_store_dwordx4 v[134:135], v[164:167], off
	v_add_co_u32_e32 v134, vcc, s26, v158
	s_nop 0
	v_cvt_pk_bf16_f32 v164, v40, v41
	v_cvt_pk_bf16_f32 v165, v42, v43
	v_cvt_pk_bf16_f32 v166, v32, v33
	v_cvt_pk_bf16_f32 v167, v34, v35
	global_store_dwordx4 v[132:133], v[164:167], off offset:-4096
	v_addc_co_u32_e32 v135, vcc, 0, v159, vcc
	s_nop 0
	v_cvt_pk_bf16_f32 v164, v20, v21
	v_cvt_pk_bf16_f32 v165, v22, v23
	v_cvt_pk_bf16_f32 v166, v12, v13
	v_cvt_pk_bf16_f32 v167, v14, v15
	global_store_dwordx4 v[134:135], v[164:167], off
	s_nop 1
	v_cvt_pk_bf16_f32 v164, v24, v25
	v_cvt_pk_bf16_f32 v165, v26, v27
	v_cvt_pk_bf16_f32 v166, v16, v17
	v_cvt_pk_bf16_f32 v167, v18, v19
	global_store_dwordx4 v[132:133], v[164:167], off
	v_add_co_u32_e32 v132, vcc, 0x1b000, v158
	s_nop 0
	v_cvt_pk_bf16_f32 v164, v8, v9
	v_cvt_pk_bf16_f32 v165, v10, v11
	v_cvt_pk_bf16_f32 v166, v4, v5
	v_cvt_pk_bf16_f32 v167, v6, v7
	s_nop 0
	v_addc_co_u32_e32 v133, vcc, 0, v159, vcc
	global_store_dwordx4 v[132:133], v[164:167], off
